# baseline (speedup 1.0000x reference)
; #define SCHED __builtin_amdgcn_sched_barrier(0)
; template <bool HS>
; __device__ __forceinline__ void gemm_tile8(const u16* __restrict__ Ap, const u16* __restrict__ Bp, int K,
;                                            f32x4 (&acc)[2][2][4][2], char* shm, const int tid, const float* hsr = nullptr) {
;     ...
;   stage_rc(tid * 16, r0, c0);
;   stage_rc(tid * 16 + 8192, r1, c1);
;   const unsigned off0 = (unsigned)(r0 * K + c0) * 2u, off1 = (unsigned)(r1 * K + c1) * 2u;
;   const int wvoff = __builtin_amdgcn_readfirstlane(tid >> 6) * 1024;
;   const u16* A1 = Ap + (size_t)128 * K;
;   const u16* B1p = Bp + (size_t)128 * K;
; #pragma unroll
;   for (int a = 0; a < 2; ++a)
; #pragma unroll
;     for (int b = 0; b < 2; ++b)
; #pragma unroll
;       for (int m = 0; m < 4; ++m)
; #pragma unroll
;         for (int n = 0; n < 2; ++n) acc[a][b][m][n] = f32x4{0.f, 0.f, 0.f, 0.f};
;   const int abase = lds_byte(wr * 64 + fr, fq * 8), bbase = lds_byte(wc * 32 + fr, fq * 8);
;   bf16x8 At[4][2], B0[2][2], B1[2][2];
;   const unsigned lds0 = (unsigned)(size_t)(__attribute__((address_space(3))) char*)shm + (unsigned)wvoff;
; template <int EPI, bool HS = false>
; __device__ __forceinline__ void gemm_phase(const Params& p, const GemmCfg& g, char* shm, const int wave_s) {
;     ...
;       u16* ot = g.o16 + (size_t)orow0 * DFF + pn * 128;
;       const unsigned tb = (unsigned)((wr * 64 + fq * 4) * DFF + wc * 16 + fr);
; #pragma unroll
;       for (int ai = 0; ai < 2; ++ai)
; #pragma unroll
;         for (int m = 0; m < 4; ++m) {
;           const f32x4 r4 = *(const f32x4*)(rsw + ai * 128 + m * 16);
; #pragma unroll
;           for (int j = 0; j < 4; ++j)
; #pragma unroll
;             for (int bj = 0; bj < 2; ++bj) {
;               float gv = r4[j] * acc[ai][bj][m][0][j] + swv[bj][0], uv = r4[j] * acc[ai][bj][m][1][j] + swv[bj][1];
;               ot[tb + (ai * 128 + m * 16 + j) * DFF + bj * 64] = f2bf(silu_f(gv) * uv);
;             }
;           SCHED;
;         }
.Lf_858:
	s_or_b64 exec, exec, s[0:1]
	v_bfe_i32 v6, v0, 27, 1
	v_lshlrev_b32_e32 v4, 4, v0
	v_lshrrev_b32_e32 v6, 22, v6
	v_add_u32_e32 v6, v4, v6
	v_and_b32_e32 v6, 0xfffffc00, v6
	v_ashrrev_i32_e32 v5, 31, v0
	v_sub_u32_e32 v6, v4, v6
	v_lshrrev_b32_e32 v5, 26, v5
	v_lshrrev_b32_e32 v7, 4, v6
	v_add_u32_e32 v5, v0, v5
	v_bitop3_b32 v7, v7, v6, 32 bitop3:0x6c
	v_ashrrev_i32_e32 v6, 31, v6
	v_ashrrev_i32_e32 v5, 6, v5
	v_lshrrev_b32_e32 v6, 26, v6
	v_lshlrev_b32_e32 v8, 3, v5
	v_add_u32_e32 v6, v7, v6
	v_and_b32_e32 v8, 0x1ffff0, v8
	v_ashrrev_i32_e32 v6, 6, v6
	v_add_u32_e32 v8, v6, v8
	v_mul_i32_i24_e32 v6, 64, v6
	v_add_u32_e32 v4, 0x2000, v4
	v_sub_u32_e32 v6, v7, v6
	v_ashrrev_i32_e32 v7, 31, v4
	v_lshrrev_b32_e32 v7, 22, v7
	v_add_u32_e32 v7, v4, v7
	v_ashrrev_i32_e32 v7, 10, v7
	v_mul_i32_i24_e32 v9, 0x400, v7
	v_sub_u32_e32 v4, v4, v9
	v_lshrrev_b32_e32 v9, 4, v4
	v_bitop3_b32 v4, v9, v4, 32 bitop3:0x6c
	v_ashrrev_i32_e32 v10, 31, v4
	v_lshrrev_b32_e32 v10, 26, v10
	v_add_u32_e32 v10, v4, v10
	v_lshlrev_b32_e32 v9, 3, v7
	v_lshrrev_b32_e32 v11, 6, v10
	v_and_b32_e32 v10, 0xc0, v10
	v_and_b32_e32 v9, 0x1ffff0, v9
	v_lshlrev_b32_e32 v7, 5, v7
	v_sub_u32_e32 v4, v4, v10
	s_ashr_i32 s5, s4, 31
	v_lshlrev_b32_e32 v5, 5, v5
	v_add_u32_e32 v9, v11, v9
	v_and_b32_e32 v7, 32, v7
	v_ashrrev_i16_sdwa v4, v178, sext(v4) dst_sel:DWORD dst_unused:UNUSED_PAD src0_sel:DWORD src1_sel:BYTE_0
	s_lshl_b64 s[0:1], s[4:5], 11
	v_and_b32_e32 v5, 32, v5
	v_ashrrev_i16_sdwa v6, v178, sext(v6) dst_sel:DWORD dst_unused:UNUSED_PAD src0_sel:DWORD src1_sel:BYTE_0
	v_bfe_i32 v4, v4, 0, 16
	v_lshl_or_b32 v7, v9, 10, v7
	s_add_u32 s5, s88, s0
	v_bfe_i32 v6, v6, 0, 16
	v_lshl_or_b32 v5, v8, 10, v5
	v_and_b32_e32 v8, 15, v0
	v_add_lshl_u32 v143, v7, v4, 1
	v_lshlrev_b32_e32 v7, 2, v0
	s_addc_u32 s6, s89, s1
	s_ashr_i32 s3, s2, 31
	v_add_lshl_u32 v144, v5, v6, 1
	v_and_b32_e32 v4, 48, v0
	v_lshlrev_b32_e32 v5, 6, v8
	v_and_b32_e32 v7, 32, v7
	s_lshl_b64 s[10:11], s[2:3], 19
	s_lshl_b32 s3, s7, 10
	v_or_b32_e32 v6, v5, v4
	v_bitop3_b32 v4, v5, v7, v4 bitop3:0x36
	v_lshlrev_b32_e32 v2, 12, v2
	s_movk_i32 s7, 0x3000
	v_lshl_add_u64 v[130:131], v[134:135], 0, s[10:11]
	s_mov_b64 s[10:11], 0x40000
	v_and_or_b32 v145, v2, s7, v4
	s_add_i32 s7, s3, 0
	v_lshl_add_u64 v[132:133], v[130:131], 0, s[10:11]
	s_add_u32 s10, s5, 0x40100
	v_lshlrev_b32_e32 v3, 13, v3
	s_addc_u32 s11, s6, 0
	v_readlane_b32 s12, v254, 34
	v_bitop3_b32 v3, v6, v3, v7 bitop3:0xde
	s_add_u32 s12, s12, s0
	v_readlane_b32 s0, v254, 35
	v_mov_b32_e32 v2, 0
	s_addc_u32 s13, s0, s1
	s_mov_b32 s14, -2
	s_mov_b64 s[0:1], 0
	v_add_u32_e32 v142, 0, v3
	s_waitcnt lgkmcnt(0)
	v_mov_b32_e32 v240, v143
	v_mov_b32_e32 v241, v144
	v_mov_b32_e32 v242, v145
	v_mov_b32_e32 v243, v142
	v_add_u32_e32 v244, 0x10000, v145
	v_add_u32_e32 v245, 0x14000, v145
	v_add_u32_e32 v246, 0x18000, v145
	v_add_u32_e32 v247, 0x1c000, v145
	s_mov_b32 s3, -1
	v_mbcnt_lo_u32_b32 v4, s3, 0
	v_mbcnt_hi_u32_b32 v4, s3, v4
	v_and_b32_e32 v5, 15, v4
	v_lshrrev_b32_e32 v6, 4, v4
	v_lshrrev_b32_e32 v7, 2, v4
	v_and_b32_e32 v8, 3, v4
	s_andn2_b32 s0, s82, 3
	s_lshl_b32 s0, s0, 6
	v_lshl_add_u32 v251, v6, 4, s0
	s_mul_i32 s0, s0, 0x580
	v_mul_u32_u24_e32 v250, 0x1600, v7
	v_add_u32_e32 v250, s0, v250
	s_and_b32 s0, s82, 3
	s_lshl_b32 s0, s0, 6
	v_lshl_add_u32 v250, v8, 4, v250
	v_add_u32_e32 v250, s0, v250
	s_lshl_b32 s0, s82, 10
	s_add_i32 s0, s0, 0x20800
	v_lshlrev_b32_e32 v248, 8, v6
	v_lshl_add_u32 v248, v5, 2, v248
	v_add_u32_e32 v248, s0, v248
	v_lshl_add_u32 v249, v4, 4, s0
	s_mov_b64 s[0:1], 0
	s_branch .Lffn_in_kinit
.LBB0_853:
	s_mul_hi_i32 s3, s4, 0x1600
	s_mulk_i32 s4, 0x1600
	s_add_u32 s4, s90, s4
	s_addc_u32 s5, s91, s3
	s_lshl_b32 s2, s2, 7
	s_ashr_i32 s3, s2, 31
	s_lshl_b64 s[2:3], s[2:3], 1
	s_add_u32 s2, s4, s2
	s_addc_u32 s3, s5, s3
	v_add_u32_e32 v142, s9, v251
	ds_read_b128 v[146:149], v142
	ds_read_b128 v[150:153], v142 offset:64
	ds_read_b128 v[154:157], v142 offset:128
	ds_read_b128 v[158:161], v142 offset:192
	ds_read_b128 v[162:165], v142 offset:512
	ds_read_b128 v[166:169], v142 offset:576
	ds_read_b128 v[170:173], v142 offset:640
	ds_read_b128 v[174:177], v142 offset:704
	s_mov_b32 s20, 0xbfb8aa3b
	s_mov_b32 s21, 0xbfb8aa3b
	s_mov_b32 s22, 1.0
	s_mov_b32 s23, 1.0
	s_waitcnt lgkmcnt(0)
	v_pk_fma_f32 v[126:127], v[126:127], v[146:147], v[140:141] op_sel_hi:[1,1,0]
	v_pk_fma_f32 v[94:95], v[94:95], v[146:147], v[138:139] op_sel_hi:[1,1,0]
	v_pk_mul_f32 v[194:195], v[126:127], s[20:21]
	v_pk_mul_f32 v[196:197], v[94:95], s[20:21]
	v_exp_f32_e32 v194, v194
	v_exp_f32_e32 v195, v195
	v_exp_f32_e32 v196, v196
	v_exp_f32_e32 v197, v197
	v_pk_fma_f32 v[122:123], v[122:123], v[146:147], v[140:141] op_sel:[0,0,1] op_sel_hi:[1,1,1]
	v_pk_fma_f32 v[90:91], v[90:91], v[146:147], v[138:139] op_sel:[0,0,1] op_sel_hi:[1,1,1]
	v_pk_add_f32 v[194:195], v[194:195], s[22:23]
	v_pk_add_f32 v[196:197], v[196:197], s[22:23]
	v_rcp_f32_e32 v194, v194
	v_rcp_f32_e32 v195, v195
	v_rcp_f32_e32 v196, v196
	v_rcp_f32_e32 v197, v197
	v_pk_mul_f32 v[126:127], v[126:127], v[194:195]
	v_pk_mul_f32 v[94:95], v[94:95], v[196:197]
	v_pk_mul_f32 v[126:127], v[122:123], v[126:127]
	v_pk_mul_f32 v[94:95], v[90:91], v[94:95]
	v_cvt_pk_bf16_f32 v190, v126, v94
	v_cvt_pk_bf16_f32 v191, v127, v95
	v_pk_fma_f32 v[128:129], v[128:129], v[148:149], v[140:141] op_sel_hi:[1,1,0]
	v_pk_fma_f32 v[96:97], v[96:97], v[148:149], v[138:139] op_sel_hi:[1,1,0]
	v_pk_mul_f32 v[194:195], v[128:129], s[20:21]
	v_pk_mul_f32 v[196:197], v[96:97], s[20:21]
	v_exp_f32_e32 v194, v194
	v_exp_f32_e32 v195, v195
	v_exp_f32_e32 v196, v196
	v_exp_f32_e32 v197, v197
	v_pk_fma_f32 v[124:125], v[124:125], v[148:149], v[140:141] op_sel:[0,0,1] op_sel_hi:[1,1,1]
	v_pk_fma_f32 v[92:93], v[92:93], v[148:149], v[138:139] op_sel:[0,0,1] op_sel_hi:[1,1,1]
	v_pk_add_f32 v[194:195], v[194:195], s[22:23]
	v_pk_add_f32 v[196:197], v[196:197], s[22:23]
	v_rcp_f32_e32 v194, v194
	v_rcp_f32_e32 v195, v195
	v_rcp_f32_e32 v196, v196
	v_rcp_f32_e32 v197, v197
	v_pk_mul_f32 v[128:129], v[128:129], v[194:195]
	v_pk_mul_f32 v[96:97], v[96:97], v[196:197]
	v_pk_mul_f32 v[128:129], v[124:125], v[128:129]
	v_pk_mul_f32 v[96:97], v[92:93], v[96:97]
	v_cvt_pk_bf16_f32 v192, v128, v96
	v_cvt_pk_bf16_f32 v193, v129, v97
	s_waitcnt lgkmcnt(0)
; #define SCHED __builtin_amdgcn_sched_barrier(0)
; template <int EPI, bool HS = false>
; __device__ __forceinline__ void gemm_phase(const Params& p, const GemmCfg& g, char* shm, const int wave_s) {
;     ...
;       u16* ot = g.o16 + (size_t)orow0 * DFF + pn * 128;
;       const unsigned tb = (unsigned)((wr * 64 + fq * 4) * DFF + wc * 16 + fr);
; #pragma unroll
;       for (int ai = 0; ai < 2; ++ai)
; #pragma unroll
;         for (int m = 0; m < 4; ++m) {
;           const f32x4 r4 = *(const f32x4*)(rsw + ai * 128 + m * 16);
; #pragma unroll
;           for (int j = 0; j < 4; ++j)
; #pragma unroll
;             for (int bj = 0; bj < 2; ++bj) {
;               float gv = r4[j] * acc[ai][bj][m][0][j] + swv[bj][0], uv = r4[j] * acc[ai][bj][m][1][j] + swv[bj][1];
;               ot[tb + (ai * 128 + m * 16 + j) * DFF + bj * 64] = f2bf(silu_f(gv) * uv);
;             }
;           SCHED;
;         }
	ds_write_b32 v248, v190
	ds_write_b32 v248, v191 offset:64
	ds_write_b32 v248, v192 offset:128
	ds_write_b32 v248, v193 offset:192
	ds_read_b128 v[180:183], v249
	v_pk_fma_f32 v[118:119], v[118:119], v[150:151], v[140:141] op_sel_hi:[1,1,0]
	v_pk_fma_f32 v[86:87], v[86:87], v[150:151], v[138:139] op_sel_hi:[1,1,0]
	v_pk_mul_f32 v[194:195], v[118:119], s[20:21]
	v_pk_mul_f32 v[196:197], v[86:87], s[20:21]
	v_exp_f32_e32 v194, v194
	v_exp_f32_e32 v195, v195
	v_exp_f32_e32 v196, v196
	v_exp_f32_e32 v197, v197
	v_pk_fma_f32 v[114:115], v[114:115], v[150:151], v[140:141] op_sel:[0,0,1] op_sel_hi:[1,1,1]
	v_pk_fma_f32 v[82:83], v[82:83], v[150:151], v[138:139] op_sel:[0,0,1] op_sel_hi:[1,1,1]
	v_pk_add_f32 v[194:195], v[194:195], s[22:23]
	v_pk_add_f32 v[196:197], v[196:197], s[22:23]
	v_rcp_f32_e32 v194, v194
	v_rcp_f32_e32 v195, v195
	v_rcp_f32_e32 v196, v196
	v_rcp_f32_e32 v197, v197
	v_pk_mul_f32 v[118:119], v[118:119], v[194:195]
	v_pk_mul_f32 v[86:87], v[86:87], v[196:197]
	v_pk_mul_f32 v[118:119], v[114:115], v[118:119]
	v_pk_mul_f32 v[86:87], v[82:83], v[86:87]
	v_cvt_pk_bf16_f32 v190, v118, v86
	v_cvt_pk_bf16_f32 v191, v119, v87
	v_pk_fma_f32 v[120:121], v[120:121], v[152:153], v[140:141] op_sel_hi:[1,1,0]
	v_pk_fma_f32 v[88:89], v[88:89], v[152:153], v[138:139] op_sel_hi:[1,1,0]
	v_pk_mul_f32 v[194:195], v[120:121], s[20:21]
	v_pk_mul_f32 v[196:197], v[88:89], s[20:21]
	v_exp_f32_e32 v194, v194
	v_exp_f32_e32 v195, v195
	v_exp_f32_e32 v196, v196
	v_exp_f32_e32 v197, v197
	v_pk_fma_f32 v[116:117], v[116:117], v[152:153], v[140:141] op_sel:[0,0,1] op_sel_hi:[1,1,1]
	v_pk_fma_f32 v[84:85], v[84:85], v[152:153], v[138:139] op_sel:[0,0,1] op_sel_hi:[1,1,1]
	v_pk_add_f32 v[194:195], v[194:195], s[22:23]
	v_pk_add_f32 v[196:197], v[196:197], s[22:23]
	v_rcp_f32_e32 v194, v194
	v_rcp_f32_e32 v195, v195
	v_rcp_f32_e32 v196, v196
	v_rcp_f32_e32 v197, v197
	v_pk_mul_f32 v[120:121], v[120:121], v[194:195]
	v_pk_mul_f32 v[88:89], v[88:89], v[196:197]
	v_pk_mul_f32 v[120:121], v[116:117], v[120:121]
	v_pk_mul_f32 v[88:89], v[84:85], v[88:89]
	v_cvt_pk_bf16_f32 v192, v120, v88
	v_cvt_pk_bf16_f32 v193, v121, v89
	s_waitcnt lgkmcnt(0)
	global_store_dwordx4 v250, v[180:183], s[2:3]
	s_add_u32 s2, s2, 0x16000
	s_addc_u32 s3, s3, 0
	ds_write_b32 v248, v190
	ds_write_b32 v248, v191 offset:64
	ds_write_b32 v248, v192 offset:128
	ds_write_b32 v248, v193 offset:192
	ds_read_b128 v[184:187], v249
	v_pk_fma_f32 v[110:111], v[110:111], v[154:155], v[140:141] op_sel_hi:[1,1,0]
	v_pk_fma_f32 v[78:79], v[78:79], v[154:155], v[138:139] op_sel_hi:[1,1,0]
	v_pk_mul_f32 v[194:195], v[110:111], s[20:21]
	v_pk_mul_f32 v[196:197], v[78:79], s[20:21]
	v_exp_f32_e32 v194, v194
	v_exp_f32_e32 v195, v195
	v_exp_f32_e32 v196, v196
	v_exp_f32_e32 v197, v197
	v_pk_fma_f32 v[106:107], v[106:107], v[154:155], v[140:141] op_sel:[0,0,1] op_sel_hi:[1,1,1]
	v_pk_fma_f32 v[74:75], v[74:75], v[154:155], v[138:139] op_sel:[0,0,1] op_sel_hi:[1,1,1]
	v_pk_add_f32 v[194:195], v[194:195], s[22:23]
	v_pk_add_f32 v[196:197], v[196:197], s[22:23]
	v_rcp_f32_e32 v194, v194
	v_rcp_f32_e32 v195, v195
	v_rcp_f32_e32 v196, v196
	v_rcp_f32_e32 v197, v197
	v_pk_mul_f32 v[110:111], v[110:111], v[194:195]
	v_pk_mul_f32 v[78:79], v[78:79], v[196:197]
	v_pk_mul_f32 v[110:111], v[106:107], v[110:111]
	v_pk_mul_f32 v[78:79], v[74:75], v[78:79]
	v_cvt_pk_bf16_f32 v190, v110, v78
	v_cvt_pk_bf16_f32 v191, v111, v79
	v_pk_fma_f32 v[112:113], v[112:113], v[156:157], v[140:141] op_sel_hi:[1,1,0]
	v_pk_fma_f32 v[80:81], v[80:81], v[156:157], v[138:139] op_sel_hi:[1,1,0]
	v_pk_mul_f32 v[194:195], v[112:113], s[20:21]
	v_pk_mul_f32 v[196:197], v[80:81], s[20:21]
	v_exp_f32_e32 v194, v194
	v_exp_f32_e32 v195, v195
	v_exp_f32_e32 v196, v196
	v_exp_f32_e32 v197, v197
	v_pk_fma_f32 v[108:109], v[108:109], v[156:157], v[140:141] op_sel:[0,0,1] op_sel_hi:[1,1,1]
	v_pk_fma_f32 v[76:77], v[76:77], v[156:157], v[138:139] op_sel:[0,0,1] op_sel_hi:[1,1,1]
	v_pk_add_f32 v[194:195], v[194:195], s[22:23]
	v_pk_add_f32 v[196:197], v[196:197], s[22:23]
	v_rcp_f32_e32 v194, v194
	v_rcp_f32_e32 v195, v195
	v_rcp_f32_e32 v196, v196
	v_rcp_f32_e32 v197, v197
	v_pk_mul_f32 v[112:113], v[112:113], v[194:195]
	v_pk_mul_f32 v[80:81], v[80:81], v[196:197]
	v_pk_mul_f32 v[112:113], v[108:109], v[112:113]
	v_pk_mul_f32 v[80:81], v[76:77], v[80:81]
	v_cvt_pk_bf16_f32 v192, v112, v80
	v_cvt_pk_bf16_f32 v193, v113, v81
	s_waitcnt lgkmcnt(0)
	global_store_dwordx4 v250, v[184:187], s[2:3]
	s_add_u32 s2, s2, 0x16000
	s_addc_u32 s3, s3, 0
	ds_write_b32 v248, v190
	ds_write_b32 v248, v191 offset:64
	ds_write_b32 v248, v192 offset:128
	ds_write_b32 v248, v193 offset:192
	ds_read_b128 v[180:183], v249
	v_pk_fma_f32 v[102:103], v[102:103], v[158:159], v[140:141] op_sel_hi:[1,1,0]
	v_pk_fma_f32 v[70:71], v[70:71], v[158:159], v[138:139] op_sel_hi:[1,1,0]
	v_pk_mul_f32 v[194:195], v[102:103], s[20:21]
	v_pk_mul_f32 v[196:197], v[70:71], s[20:21]
	v_exp_f32_e32 v194, v194
	v_exp_f32_e32 v195, v195
	v_exp_f32_e32 v196, v196
	v_exp_f32_e32 v197, v197
	v_pk_fma_f32 v[98:99], v[98:99], v[158:159], v[140:141] op_sel:[0,0,1] op_sel_hi:[1,1,1]
	v_pk_fma_f32 v[66:67], v[66:67], v[158:159], v[138:139] op_sel:[0,0,1] op_sel_hi:[1,1,1]
	v_pk_add_f32 v[194:195], v[194:195], s[22:23]
	v_pk_add_f32 v[196:197], v[196:197], s[22:23]
	v_rcp_f32_e32 v194, v194
	v_rcp_f32_e32 v195, v195
	v_rcp_f32_e32 v196, v196
	v_rcp_f32_e32 v197, v197
	v_pk_mul_f32 v[102:103], v[102:103], v[194:195]
	v_pk_mul_f32 v[70:71], v[70:71], v[196:197]
	v_pk_mul_f32 v[102:103], v[98:99], v[102:103]
	v_pk_mul_f32 v[70:71], v[66:67], v[70:71]
	v_cvt_pk_bf16_f32 v190, v102, v70
	v_cvt_pk_bf16_f32 v191, v103, v71
	v_pk_fma_f32 v[104:105], v[104:105], v[160:161], v[140:141] op_sel_hi:[1,1,0]
	v_pk_fma_f32 v[72:73], v[72:73], v[160:161], v[138:139] op_sel_hi:[1,1,0]
	v_pk_mul_f32 v[194:195], v[104:105], s[20:21]
	v_pk_mul_f32 v[196:197], v[72:73], s[20:21]
	v_exp_f32_e32 v194, v194
	v_exp_f32_e32 v195, v195
	v_exp_f32_e32 v196, v196
	v_exp_f32_e32 v197, v197
	v_pk_fma_f32 v[100:101], v[100:101], v[160:161], v[140:141] op_sel:[0,0,1] op_sel_hi:[1,1,1]
	v_pk_fma_f32 v[68:69], v[68:69], v[160:161], v[138:139] op_sel:[0,0,1] op_sel_hi:[1,1,1]
	v_pk_add_f32 v[194:195], v[194:195], s[22:23]
	v_pk_add_f32 v[196:197], v[196:197], s[22:23]
	v_rcp_f32_e32 v194, v194
	v_rcp_f32_e32 v195, v195
	v_rcp_f32_e32 v196, v196
	v_rcp_f32_e32 v197, v197
	v_pk_mul_f32 v[104:105], v[104:105], v[194:195]
	v_pk_mul_f32 v[72:73], v[72:73], v[196:197]
	v_pk_mul_f32 v[104:105], v[100:101], v[104:105]
	v_pk_mul_f32 v[72:73], v[68:69], v[72:73]
	v_cvt_pk_bf16_f32 v192, v104, v72
	v_cvt_pk_bf16_f32 v193, v105, v73
	s_waitcnt lgkmcnt(0)
; #define SCHED __builtin_amdgcn_sched_barrier(0)
; template <int EPI, bool HS = false>
; __device__ __forceinline__ void gemm_phase(const Params& p, const GemmCfg& g, char* shm, const int wave_s) {
;     ...
;       u16* ot = g.o16 + (size_t)orow0 * DFF + pn * 128;
;       const unsigned tb = (unsigned)((wr * 64 + fq * 4) * DFF + wc * 16 + fr);
; #pragma unroll
;       for (int ai = 0; ai < 2; ++ai)
; #pragma unroll
;         for (int m = 0; m < 4; ++m) {
;           const f32x4 r4 = *(const f32x4*)(rsw + ai * 128 + m * 16);
; #pragma unroll
;           for (int j = 0; j < 4; ++j)
; #pragma unroll
;             for (int bj = 0; bj < 2; ++bj) {
;               float gv = r4[j] * acc[ai][bj][m][0][j] + swv[bj][0], uv = r4[j] * acc[ai][bj][m][1][j] + swv[bj][1];
;               ot[tb + (ai * 128 + m * 16 + j) * DFF + bj * 64] = f2bf(silu_f(gv) * uv);
;             }
;           SCHED;
;         }
	global_store_dwordx4 v250, v[180:183], s[2:3]
	s_add_u32 s2, s2, 0x16000
	s_addc_u32 s3, s3, 0
	ds_write_b32 v248, v190
	ds_write_b32 v248, v191 offset:64
	ds_write_b32 v248, v192 offset:128
	ds_write_b32 v248, v193 offset:192
	ds_read_b128 v[184:187], v249
	v_pk_fma_f32 v[62:63], v[62:63], v[162:163], v[140:141] op_sel_hi:[1,1,0]
	v_pk_fma_f32 v[30:31], v[30:31], v[162:163], v[138:139] op_sel_hi:[1,1,0]
	v_pk_mul_f32 v[194:195], v[62:63], s[20:21]
	v_pk_mul_f32 v[196:197], v[30:31], s[20:21]
	v_exp_f32_e32 v194, v194
	v_exp_f32_e32 v195, v195
	v_exp_f32_e32 v196, v196
	v_exp_f32_e32 v197, v197
	v_pk_fma_f32 v[58:59], v[58:59], v[162:163], v[140:141] op_sel:[0,0,1] op_sel_hi:[1,1,1]
	v_pk_fma_f32 v[26:27], v[26:27], v[162:163], v[138:139] op_sel:[0,0,1] op_sel_hi:[1,1,1]
	v_pk_add_f32 v[194:195], v[194:195], s[22:23]
	v_pk_add_f32 v[196:197], v[196:197], s[22:23]
	v_rcp_f32_e32 v194, v194
	v_rcp_f32_e32 v195, v195
	v_rcp_f32_e32 v196, v196
	v_rcp_f32_e32 v197, v197
	v_pk_mul_f32 v[62:63], v[62:63], v[194:195]
	v_pk_mul_f32 v[30:31], v[30:31], v[196:197]
	v_pk_mul_f32 v[62:63], v[58:59], v[62:63]
	v_pk_mul_f32 v[30:31], v[26:27], v[30:31]
	v_cvt_pk_bf16_f32 v190, v62, v30
	v_cvt_pk_bf16_f32 v191, v63, v31
	v_pk_fma_f32 v[64:65], v[64:65], v[164:165], v[140:141] op_sel_hi:[1,1,0]
	v_pk_fma_f32 v[32:33], v[32:33], v[164:165], v[138:139] op_sel_hi:[1,1,0]
	v_pk_mul_f32 v[194:195], v[64:65], s[20:21]
	v_pk_mul_f32 v[196:197], v[32:33], s[20:21]
	v_exp_f32_e32 v194, v194
	v_exp_f32_e32 v195, v195
	v_exp_f32_e32 v196, v196
	v_exp_f32_e32 v197, v197
	v_pk_fma_f32 v[60:61], v[60:61], v[164:165], v[140:141] op_sel:[0,0,1] op_sel_hi:[1,1,1]
	v_pk_fma_f32 v[28:29], v[28:29], v[164:165], v[138:139] op_sel:[0,0,1] op_sel_hi:[1,1,1]
	v_pk_add_f32 v[194:195], v[194:195], s[22:23]
	v_pk_add_f32 v[196:197], v[196:197], s[22:23]
	v_rcp_f32_e32 v194, v194
	v_rcp_f32_e32 v195, v195
	v_rcp_f32_e32 v196, v196
	v_rcp_f32_e32 v197, v197
	v_pk_mul_f32 v[64:65], v[64:65], v[194:195]
	v_pk_mul_f32 v[32:33], v[32:33], v[196:197]
	v_pk_mul_f32 v[64:65], v[60:61], v[64:65]
	v_pk_mul_f32 v[32:33], v[28:29], v[32:33]
	v_cvt_pk_bf16_f32 v192, v64, v32
	v_cvt_pk_bf16_f32 v193, v65, v33
	s_waitcnt lgkmcnt(0)
	global_store_dwordx4 v250, v[184:187], s[2:3]
	s_add_u32 s2, s2, 0x6e000
	s_addc_u32 s3, s3, 0
	ds_write_b32 v248, v190
	ds_write_b32 v248, v191 offset:64
	ds_write_b32 v248, v192 offset:128
	ds_write_b32 v248, v193 offset:192
	ds_read_b128 v[180:183], v249
	v_pk_fma_f32 v[54:55], v[54:55], v[166:167], v[140:141] op_sel_hi:[1,1,0]
	v_pk_fma_f32 v[22:23], v[22:23], v[166:167], v[138:139] op_sel_hi:[1,1,0]
	v_pk_mul_f32 v[194:195], v[54:55], s[20:21]
	v_pk_mul_f32 v[196:197], v[22:23], s[20:21]
	v_exp_f32_e32 v194, v194
	v_exp_f32_e32 v195, v195
	v_exp_f32_e32 v196, v196
	v_exp_f32_e32 v197, v197
	v_pk_fma_f32 v[50:51], v[50:51], v[166:167], v[140:141] op_sel:[0,0,1] op_sel_hi:[1,1,1]
	v_pk_fma_f32 v[18:19], v[18:19], v[166:167], v[138:139] op_sel:[0,0,1] op_sel_hi:[1,1,1]
	v_pk_add_f32 v[194:195], v[194:195], s[22:23]
	v_pk_add_f32 v[196:197], v[196:197], s[22:23]
	v_rcp_f32_e32 v194, v194
	v_rcp_f32_e32 v195, v195
	v_rcp_f32_e32 v196, v196
	v_rcp_f32_e32 v197, v197
	v_pk_mul_f32 v[54:55], v[54:55], v[194:195]
	v_pk_mul_f32 v[22:23], v[22:23], v[196:197]
	v_pk_mul_f32 v[54:55], v[50:51], v[54:55]
	v_pk_mul_f32 v[22:23], v[18:19], v[22:23]
	v_cvt_pk_bf16_f32 v190, v54, v22
	v_cvt_pk_bf16_f32 v191, v55, v23
	v_pk_fma_f32 v[56:57], v[56:57], v[168:169], v[140:141] op_sel_hi:[1,1,0]
	v_pk_fma_f32 v[24:25], v[24:25], v[168:169], v[138:139] op_sel_hi:[1,1,0]
	v_pk_mul_f32 v[194:195], v[56:57], s[20:21]
	v_pk_mul_f32 v[196:197], v[24:25], s[20:21]
	v_exp_f32_e32 v194, v194
	v_exp_f32_e32 v195, v195
	v_exp_f32_e32 v196, v196
	v_exp_f32_e32 v197, v197
	v_pk_fma_f32 v[52:53], v[52:53], v[168:169], v[140:141] op_sel:[0,0,1] op_sel_hi:[1,1,1]
	v_pk_fma_f32 v[20:21], v[20:21], v[168:169], v[138:139] op_sel:[0,0,1] op_sel_hi:[1,1,1]
	v_pk_add_f32 v[194:195], v[194:195], s[22:23]
	v_pk_add_f32 v[196:197], v[196:197], s[22:23]
	v_rcp_f32_e32 v194, v194
	v_rcp_f32_e32 v195, v195
	v_rcp_f32_e32 v196, v196
	v_rcp_f32_e32 v197, v197
	v_pk_mul_f32 v[56:57], v[56:57], v[194:195]
	v_pk_mul_f32 v[24:25], v[24:25], v[196:197]
	v_pk_mul_f32 v[56:57], v[52:53], v[56:57]
	v_pk_mul_f32 v[24:25], v[20:21], v[24:25]
	v_cvt_pk_bf16_f32 v192, v56, v24
	v_cvt_pk_bf16_f32 v193, v57, v25
	s_waitcnt lgkmcnt(0)
; #define SCHED __builtin_amdgcn_sched_barrier(0)
; template <int EPI, bool HS = false>
; __device__ __forceinline__ void gemm_phase(const Params& p, const GemmCfg& g, char* shm, const int wave_s) {
;     ...
;       u16* ot = g.o16 + (size_t)orow0 * DFF + pn * 128;
;       const unsigned tb = (unsigned)((wr * 64 + fq * 4) * DFF + wc * 16 + fr);
; #pragma unroll
;       for (int ai = 0; ai < 2; ++ai)
; #pragma unroll
;         for (int m = 0; m < 4; ++m) {
;           const f32x4 r4 = *(const f32x4*)(rsw + ai * 128 + m * 16);
; #pragma unroll
;           for (int j = 0; j < 4; ++j)
; #pragma unroll
;             for (int bj = 0; bj < 2; ++bj) {
;               float gv = r4[j] * acc[ai][bj][m][0][j] + swv[bj][0], uv = r4[j] * acc[ai][bj][m][1][j] + swv[bj][1];
;               ot[tb + (ai * 128 + m * 16 + j) * DFF + bj * 64] = f2bf(silu_f(gv) * uv);
;             }
;           SCHED;
;         }
	global_store_dwordx4 v250, v[180:183], s[2:3]
	s_add_u32 s2, s2, 0x16000
	s_addc_u32 s3, s3, 0
	ds_write_b32 v248, v190
	ds_write_b32 v248, v191 offset:64
	ds_write_b32 v248, v192 offset:128
	ds_write_b32 v248, v193 offset:192
	ds_read_b128 v[184:187], v249
	v_pk_fma_f32 v[46:47], v[46:47], v[170:171], v[140:141] op_sel_hi:[1,1,0]
	v_pk_fma_f32 v[14:15], v[14:15], v[170:171], v[138:139] op_sel_hi:[1,1,0]
	v_pk_mul_f32 v[194:195], v[46:47], s[20:21]
	v_pk_mul_f32 v[196:197], v[14:15], s[20:21]
	v_exp_f32_e32 v194, v194
	v_exp_f32_e32 v195, v195
	v_exp_f32_e32 v196, v196
	v_exp_f32_e32 v197, v197
	v_pk_fma_f32 v[42:43], v[42:43], v[170:171], v[140:141] op_sel:[0,0,1] op_sel_hi:[1,1,1]
	v_pk_fma_f32 v[10:11], v[10:11], v[170:171], v[138:139] op_sel:[0,0,1] op_sel_hi:[1,1,1]
	v_pk_add_f32 v[194:195], v[194:195], s[22:23]
	v_pk_add_f32 v[196:197], v[196:197], s[22:23]
	v_rcp_f32_e32 v194, v194
	v_rcp_f32_e32 v195, v195
	v_rcp_f32_e32 v196, v196
	v_rcp_f32_e32 v197, v197
	v_pk_mul_f32 v[46:47], v[46:47], v[194:195]
	v_pk_mul_f32 v[14:15], v[14:15], v[196:197]
	v_pk_mul_f32 v[46:47], v[42:43], v[46:47]
	v_pk_mul_f32 v[14:15], v[10:11], v[14:15]
	v_cvt_pk_bf16_f32 v190, v46, v14
	v_cvt_pk_bf16_f32 v191, v47, v15
	v_pk_fma_f32 v[48:49], v[48:49], v[172:173], v[140:141] op_sel_hi:[1,1,0]
	v_pk_fma_f32 v[16:17], v[16:17], v[172:173], v[138:139] op_sel_hi:[1,1,0]
	v_pk_mul_f32 v[194:195], v[48:49], s[20:21]
	v_pk_mul_f32 v[196:197], v[16:17], s[20:21]
	v_exp_f32_e32 v194, v194
	v_exp_f32_e32 v195, v195
	v_exp_f32_e32 v196, v196
	v_exp_f32_e32 v197, v197
	v_pk_fma_f32 v[44:45], v[44:45], v[172:173], v[140:141] op_sel:[0,0,1] op_sel_hi:[1,1,1]
	v_pk_fma_f32 v[12:13], v[12:13], v[172:173], v[138:139] op_sel:[0,0,1] op_sel_hi:[1,1,1]
	v_pk_add_f32 v[194:195], v[194:195], s[22:23]
	v_pk_add_f32 v[196:197], v[196:197], s[22:23]
	v_rcp_f32_e32 v194, v194
	v_rcp_f32_e32 v195, v195
	v_rcp_f32_e32 v196, v196
	v_rcp_f32_e32 v197, v197
	v_pk_mul_f32 v[48:49], v[48:49], v[194:195]
	v_pk_mul_f32 v[16:17], v[16:17], v[196:197]
	v_pk_mul_f32 v[48:49], v[44:45], v[48:49]
	v_pk_mul_f32 v[16:17], v[12:13], v[16:17]
	v_cvt_pk_bf16_f32 v192, v48, v16
	v_cvt_pk_bf16_f32 v193, v49, v17
	s_waitcnt lgkmcnt(0)
	global_store_dwordx4 v250, v[184:187], s[2:3]
	s_add_u32 s2, s2, 0x16000
	s_addc_u32 s3, s3, 0
	ds_write_b32 v248, v190
	ds_write_b32 v248, v191 offset:64
	ds_write_b32 v248, v192 offset:128
	ds_write_b32 v248, v193 offset:192
	ds_read_b128 v[180:183], v249
	v_pk_fma_f32 v[38:39], v[38:39], v[174:175], v[140:141] op_sel_hi:[1,1,0]
	v_pk_fma_f32 v[6:7], v[6:7], v[174:175], v[138:139] op_sel_hi:[1,1,0]
	v_pk_mul_f32 v[194:195], v[38:39], s[20:21]
	v_pk_mul_f32 v[196:197], v[6:7], s[20:21]
	v_exp_f32_e32 v194, v194
	v_exp_f32_e32 v195, v195
	v_exp_f32_e32 v196, v196
	v_exp_f32_e32 v197, v197
	v_pk_fma_f32 v[34:35], v[34:35], v[174:175], v[140:141] op_sel:[0,0,1] op_sel_hi:[1,1,1]
	v_pk_fma_f32 v[2:3], v[2:3], v[174:175], v[138:139] op_sel:[0,0,1] op_sel_hi:[1,1,1]
	v_pk_add_f32 v[194:195], v[194:195], s[22:23]
	v_pk_add_f32 v[196:197], v[196:197], s[22:23]
	v_rcp_f32_e32 v194, v194
	v_rcp_f32_e32 v195, v195
	v_rcp_f32_e32 v196, v196
	v_rcp_f32_e32 v197, v197
	v_pk_mul_f32 v[38:39], v[38:39], v[194:195]
	v_pk_mul_f32 v[6:7], v[6:7], v[196:197]
	v_pk_mul_f32 v[38:39], v[34:35], v[38:39]
	v_pk_mul_f32 v[6:7], v[2:3], v[6:7]
	v_cvt_pk_bf16_f32 v190, v38, v6
	v_cvt_pk_bf16_f32 v191, v39, v7
	v_pk_fma_f32 v[40:41], v[40:41], v[176:177], v[140:141] op_sel_hi:[1,1,0]
	v_pk_fma_f32 v[8:9], v[8:9], v[176:177], v[138:139] op_sel_hi:[1,1,0]
	v_pk_mul_f32 v[194:195], v[40:41], s[20:21]
	v_pk_mul_f32 v[196:197], v[8:9], s[20:21]
	v_exp_f32_e32 v194, v194
	v_exp_f32_e32 v195, v195
	v_exp_f32_e32 v196, v196
	v_exp_f32_e32 v197, v197
	v_pk_fma_f32 v[36:37], v[36:37], v[176:177], v[140:141] op_sel:[0,0,1] op_sel_hi:[1,1,1]
	v_pk_fma_f32 v[4:5], v[4:5], v[176:177], v[138:139] op_sel:[0,0,1] op_sel_hi:[1,1,1]
	v_pk_add_f32 v[194:195], v[194:195], s[22:23]
	v_pk_add_f32 v[196:197], v[196:197], s[22:23]
	v_rcp_f32_e32 v194, v194
	v_rcp_f32_e32 v195, v195
	v_rcp_f32_e32 v196, v196
	v_rcp_f32_e32 v197, v197
	v_pk_mul_f32 v[40:41], v[40:41], v[194:195]
	v_pk_mul_f32 v[8:9], v[8:9], v[196:197]
	v_pk_mul_f32 v[40:41], v[36:37], v[40:41]
	v_pk_mul_f32 v[8:9], v[4:5], v[8:9]
	v_cvt_pk_bf16_f32 v192, v40, v8
	v_cvt_pk_bf16_f32 v193, v41, v9
	s_waitcnt lgkmcnt(0)
	global_store_dwordx4 v250, v[180:183], s[2:3]
	s_add_u32 s2, s2, 0x16000
	s_addc_u32 s3, s3, 0
	ds_write_b32 v248, v190
	ds_write_b32 v248, v191 offset:64
	ds_write_b32 v248, v192 offset:128
	ds_write_b32 v248, v193 offset:192
	ds_read_b128 v[184:187], v249
	s_waitcnt lgkmcnt(0)
	global_store_dwordx4 v250, v[184:187], s[2:3]
	s_and_b64 vcc, exec, s[0:1]
	s_cbranch_vccnz .LBB0_864
